# cumsumlds: FoX cumsum unit loads coalesced (32 B lane stride) and transposed through a padded LDS image instead of 512 B-stride loads (tail of the pass-1 phase)
# baseline (speedup 1.0000x reference)
; __device__ __forceinline__ void fox_cumsum_unit(Frame& F, int bh) {
;     ...
;     float v[16]; float run = 0.f;
; #pragma unroll
;     for (int i = 0; i < 16; ++i) v[i] = FFp[(size_t)(b * SEQ + F.tid * 16 + i) * 8 + h];
; #pragma unroll
;     for (int i = 0; i < 16; ++i) { run += v[i]; v[i] = run; }
;     float inc = run;
; #pragma unroll
;     for (int o = 1; o < 64; o <<= 1) { const float t = __shfl_up(inc, o); if (F.lane >= o) inc += t; }
;     if (F.lane == 63) wt[F.wave] = inc;
;     __syncthreads();
;     float base = inc - run;
;     for (int w = 0; w < F.wave; ++w) base += wt[w];
; #pragma unroll
;     for (int i4 = 0; i4 < 4; ++i4) { f32x4 o4;
; #pragma unroll
;         for (int i = 0; i < 4; ++i) o4[i] = base + v[i4 * 4 + i];
;         *(f32x4*)(C2 + (size_t)bh * SEQ + F.tid * 16 + i4 * 4) = o4; }
.LBB0_521:
	s_add_i32 s45, s44, 0xfffffc00
	s_lshl_b32 s68, s45, 10
	s_and_b32 s2, s44, 7
	s_and_b32 s68, s68, 0x2000
	s_lshl_b32 s2, s2, 2
	s_add_u32 s82, s89, s2
	s_addc_u32 s83, s90, 0
	v_add_u32_e32 v0, s68, v203
	v_lshlrev_b32_e32 v0, 5, v0
	global_load_dword v4, v0, s[82:83]
	s_add_u32 s82, s82, 0x4000
	s_addc_u32 s83, s83, 0
	global_load_dword v5, v0, s[82:83]
	s_add_u32 s82, s82, 0x4000
	s_addc_u32 s83, s83, 0
	global_load_dword v6, v0, s[82:83]
	s_add_u32 s82, s82, 0x4000
	s_addc_u32 s83, s83, 0
	global_load_dword v7, v0, s[82:83]
	s_add_u32 s82, s82, 0x4000
	s_addc_u32 s83, s83, 0
	global_load_dword v33, v0, s[82:83]
	s_add_u32 s82, s82, 0x4000
	s_addc_u32 s83, s83, 0
	global_load_dword v35, v0, s[82:83]
	s_add_u32 s82, s82, 0x4000
	s_addc_u32 s83, s83, 0
	global_load_dword v37, v0, s[82:83]
	s_add_u32 s82, s82, 0x4000
	s_addc_u32 s83, s83, 0
	global_load_dword v39, v0, s[82:83]
	s_add_u32 s82, s82, 0x4000
	s_addc_u32 s83, s83, 0
	global_load_dword v41, v0, s[82:83]
	s_add_u32 s82, s82, 0x4000
	s_addc_u32 s83, s83, 0
	global_load_dword v43, v0, s[82:83]
	s_add_u32 s82, s82, 0x4000
	s_addc_u32 s83, s83, 0
	global_load_dword v45, v0, s[82:83]
	s_add_u32 s82, s82, 0x4000
	s_addc_u32 s83, s83, 0
	global_load_dword v47, v0, s[82:83]
	s_add_u32 s82, s82, 0x4000
	s_addc_u32 s83, s83, 0
	global_load_dword v56, v0, s[82:83]
	s_add_u32 s82, s82, 0x4000
	s_addc_u32 s83, s83, 0
	global_load_dword v57, v0, s[82:83]
	s_add_u32 s82, s82, 0x4000
	s_addc_u32 s83, s83, 0
	global_load_dword v2, v0, s[82:83]
	s_add_u32 s82, s82, 0x4000
	s_addc_u32 s83, s83, 0
	global_load_dword v3, v0, s[82:83]
	v_lshrrev_b32_e32 v1, 4, v203
	v_add_u32_e32 v1, v1, v203
	v_lshlrev_b32_e32 v1, 2, v1
	v_add_u32_e32 v1, 0x400, v1
	v_add_u32_e32 v1, s69, v1
	s_waitcnt vmcnt(15)
	ds_write_b32 v1, v4
	s_waitcnt vmcnt(14)
	ds_write_b32 v1, v5 offset:2176
	s_waitcnt vmcnt(13)
	ds_write_b32 v1, v6 offset:4352
	s_waitcnt vmcnt(12)
	ds_write_b32 v1, v7 offset:6528
	s_waitcnt vmcnt(11)
	ds_write_b32 v1, v33 offset:8704
	s_waitcnt vmcnt(10)
	ds_write_b32 v1, v35 offset:10880
	s_waitcnt vmcnt(9)
	ds_write_b32 v1, v37 offset:13056
	s_waitcnt vmcnt(8)
	ds_write_b32 v1, v39 offset:15232
	s_waitcnt vmcnt(7)
	ds_write_b32 v1, v41 offset:17408
	s_waitcnt vmcnt(6)
	ds_write_b32 v1, v43 offset:19584
	s_waitcnt vmcnt(5)
	ds_write_b32 v1, v45 offset:21760
	s_waitcnt vmcnt(4)
	ds_write_b32 v1, v47 offset:23936
	s_waitcnt vmcnt(3)
	ds_write_b32 v1, v56 offset:26112
	s_waitcnt vmcnt(2)
	ds_write_b32 v1, v57 offset:28288
	s_waitcnt vmcnt(1)
	ds_write_b32 v1, v2 offset:30464
	s_waitcnt vmcnt(0)
	ds_write_b32 v1, v3 offset:32640
	s_waitcnt lgkmcnt(0)
	s_barrier
	v_mul_u32_u24_e32 v1, 0x44, v203
	v_add_u32_e32 v1, 0x400, v1
	v_add_u32_e32 v1, s69, v1
	ds_read_b32 v4, v1
	ds_read_b32 v5, v1 offset:4
	ds_read_b32 v6, v1 offset:8
	ds_read_b32 v7, v1 offset:12
	ds_read_b32 v33, v1 offset:16
	ds_read_b32 v35, v1 offset:20
	ds_read_b32 v37, v1 offset:24
	ds_read_b32 v39, v1 offset:28
	ds_read_b32 v41, v1 offset:32
	ds_read_b32 v43, v1 offset:36
	ds_read_b32 v45, v1 offset:40
	ds_read_b32 v47, v1 offset:44
	ds_read_b32 v56, v1 offset:48
	ds_read_b32 v57, v1 offset:52
	ds_read_b32 v2, v1 offset:56
	ds_read_b32 v3, v1 offset:60
	s_waitcnt vmcnt(0) lgkmcnt(0)
	v_add_f32_e32 v52, 0, v4
	v_add_f32_e32 v53, v52, v5
	v_add_f32_e32 v54, v53, v6
	v_add_f32_e32 v55, v54, v7
	v_add_f32_e32 v48, v55, v33
	v_add_u32_e32 v33, -1, v215
	v_add_f32_e32 v49, v48, v35
	v_and_b32_e32 v35, 64, v215
	v_cmp_lt_i32_e32 vcc, v33, v35
	v_add_f32_e32 v50, v49, v37
	s_nop 0
	v_cndmask_b32_e32 v33, v33, v215, vcc
	v_lshlrev_b32_e32 v33, 2, v33
	v_add_u32_e32 v37, -2, v215
	v_cmp_lt_i32_e32 vcc, v37, v35
	v_add_f32_e32 v51, v50, v39
	v_add_f32_e32 v4, v51, v41
	v_cndmask_b32_e32 v37, v37, v215, vcc
	v_lshlrev_b32_e32 v37, 2, v37
	v_add_f32_e32 v5, v4, v43
	v_add_f32_e32 v6, v5, v45
	v_add_f32_e32 v7, v6, v47
	v_add_f32_e32 v0, v7, v56
	v_add_f32_e32 v1, v0, v57
	v_add_f32_e32 v2, v1, v2
	v_add_f32_e32 v3, v2, v3
	ds_bpermute_b32 v33, v33, v3
	s_waitcnt lgkmcnt(0)
	v_add_f32_e32 v33, v3, v33
	v_cndmask_b32_e64 v33, v33, v3, s[4:5]
	ds_bpermute_b32 v37, v37, v33
	s_waitcnt lgkmcnt(0)
	v_add_f32_e32 v37, v33, v37
	v_cndmask_b32_e64 v33, v37, v33, s[6:7]
	v_add_u32_e32 v37, -4, v215
	v_cmp_lt_i32_e32 vcc, v37, v35
	s_nop 1
	v_cndmask_b32_e32 v37, v37, v215, vcc
	v_lshlrev_b32_e32 v37, 2, v37
	ds_bpermute_b32 v37, v37, v33
	s_waitcnt lgkmcnt(0)
	v_add_f32_e32 v37, v33, v37
	v_cndmask_b32_e64 v33, v37, v33, s[8:9]
	v_add_u32_e32 v37, -8, v215
	v_cmp_lt_i32_e32 vcc, v37, v35
	s_nop 1
	v_cndmask_b32_e32 v37, v37, v215, vcc
	v_lshlrev_b32_e32 v37, 2, v37
	ds_bpermute_b32 v37, v37, v33
	s_waitcnt lgkmcnt(0)
	v_add_f32_e32 v37, v33, v37
	v_cndmask_b32_e64 v33, v37, v33, s[10:11]
	v_add_u32_e32 v37, -16, v215
	v_cmp_lt_i32_e32 vcc, v37, v35
	s_nop 1
	v_cndmask_b32_e32 v37, v37, v215, vcc
	v_lshlrev_b32_e32 v37, 2, v37
	ds_bpermute_b32 v37, v37, v33
	s_waitcnt lgkmcnt(0)
	v_add_f32_e32 v37, v33, v37
	v_cndmask_b32_e64 v33, v37, v33, s[12:13]
	v_subrev_u32_e32 v37, 32, v215
	v_cmp_lt_i32_e32 vcc, v37, v35
	s_nop 1
	v_cndmask_b32_e32 v35, v37, v215, vcc
	v_lshlrev_b32_e32 v35, 2, v35
	ds_bpermute_b32 v35, v35, v33
	s_waitcnt lgkmcnt(0)
	v_add_f32_e32 v35, v33, v35
	s_and_saveexec_b64 s[82:83], s[16:17]
	v_mov_b32_e32 v37, s91
	ds_write_b32 v37, v35
	s_or_b64 exec, exec, s[82:83]
	v_cndmask_b32_e64 v33, v35, v33, s[14:15]
	v_sub_f32_e32 v56, v33, v3
	s_andn2_b64 vcc, exec, s[50:51]
	s_mov_b32 s2, s1
	s_mov_b32 s68, s72
	s_waitcnt lgkmcnt(0)
	s_barrier
	s_cbranch_vccnz .LBB0_525
